# v32: v26 + one static s_setprio 1 for waves 4-7 during the P3 attention section (timing only)
# speedup vs baseline: 1.0062x; 1.0033x over previous
; #define LAS __attribute__((address_space(3)))
; __global__ void __launch_bounds__(512, 2) mega_fwd(Args args) {
;     ...
;         __syncthreads();
;         {   LAS unsigned char* vl = lds + wave * (32 * VP);
;             constexpr int NU_S = 32 * 72;
;             for (int u = gw; u < NU_S; u += NGW) {
.LBB0_407:
	s_cmp_ge_u32 s80, 4
	s_cbranch_scc0 .Lp3_prio_done
	s_setprio 1

; __device__ __forceinline__ unsigned xb_ld(unsigned* p)              { return __hip_atomic_load(p, __ATOMIC_RELAXED, __HIP_MEMORY_SCOPE_AGENT); }
; __device__ __forceinline__ void xcd_barrier_complete(unsigned* bar, unsigned x, unsigned& nloc, unsigned& nx) {
;     const unsigned G = gridDim.x * gridDim.y * gridDim.z;
;     unsigned sum, cnt, mine, sp = 0u;
;     for (;;) {
;         sum = 0u; cnt = 0u; mine = 0u;
; #pragma unroll
;         for (unsigned j = 0; j < 16; ++j) { const unsigned c = xb_ld(&bar[XB_XCNT(j)]); sum += c; cnt += (c > 0u) ? 1u : 0u; mine = (j == x) ? c : mine; }
; __device__ __forceinline__ void xcd_barrier(const XcdBarrier& b) {
;     asm volatile("s_waitcnt vmcnt(0)" ::: "memory");
;     __syncthreads();
;     if (threadIdx.x == 0) {
;         unsigned* bar = b.bar;
;         __builtin_amdgcn_s_waitcnt(0);
;         unsigned nloc = b.st[0], nx = b.st[1];
;         if (nloc == 0u) { xcd_barrier_complete(bar, b.x, nloc, nx); b.st[0] = nloc; b.st[1] = nx; }
.LBB0_447:
	s_setprio 0
	s_and_b64 vcc, exec, s[42:43]
	s_cbranch_vccz .LBB0_460
	s_mov_b64 s[4:5], 0
	s_cmp_lg_u32 s26, 0
	s_mov_b64 s[6:7], 0
	s_cbranch_scc0 .LBB0_461
	s_waitcnt vmcnt(0)
	s_waitcnt vmcnt(0)
	s_barrier
	s_and_saveexec_b64 s[6:7], s[86:87]
	s_cbranch_execz .LBB0_1360
	s_add_i32 s8, 0, 0x23ff0
	v_mov_b32_e32 v0, s8
	s_waitcnt vmcnt(0) expcnt(0) lgkmcnt(0)
	ds_read_b32 v2, v0
	s_add_i32 s8, 0, 0x23ff4
	v_mov_b32_e32 v0, s8
	ds_read_b32 v0, v0
	s_waitcnt lgkmcnt(1)
	v_cmp_ne_u32_e32 vcc, 0, v2
	s_cbranch_vccnz .LBB0_978
	s_load_dwordx2 s[12:13], s[82:83], 0x4
	s_add_u32 s8, s36, 0x2f000200
	s_addc_u32 s9, s37, 0
	s_add_u32 s10, s36, 0x2f000400
	s_addc_u32 s11, s37, 0
	s_waitcnt lgkmcnt(0)
	s_mul_i32 s27, s12, s3
	s_add_u32 s12, s36, 0x2f000500
	s_mul_i32 s27, s27, s13
	s_addc_u32 s13, s37, 0
	s_add_u32 s14, s36, 0x2f000600
	s_addc_u32 s15, s37, 0
	s_add_u32 s18, s36, 0x2f000700
	s_addc_u32 s19, s37, 0
	s_add_u32 s20, s36, 0x2f000800
	s_addc_u32 s21, s37, 0
	s_add_u32 s22, s36, 0x2f000900
	s_addc_u32 s23, s37, 0
	s_add_u32 s28, s36, 0x2f000a00
	s_addc_u32 s29, s37, 0
	s_add_u32 s30, s36, 0x2f000b00
	s_addc_u32 s31, s37, 0
	s_add_u32 s44, s36, 0x2f000c00
	s_addc_u32 s45, s37, 0
	s_add_u32 s46, s36, 0x2f000d00
	s_addc_u32 s47, s37, 0
	s_add_u32 s48, s36, 0x2f000e00
	s_addc_u32 s49, s37, 0
	s_add_u32 s50, s36, 0x2f000f00
	s_addc_u32 s51, s37, 0
	s_add_u32 s52, s36, 0x2f001000
	s_addc_u32 s53, s37, 0
	s_add_u32 s54, s36, 0x2f001100
	s_addc_u32 s55, s37, 0
	s_add_u32 s56, s36, 0x2f001200
	s_addc_u32 s57, s37, 0
	s_add_u32 s58, s36, 0x2f001300
	s_addc_u32 s59, s37, 0
	s_mov_b32 s33, 1
	v_mov_b32_e32 v16, 0
	s_branch .LBB0_453
